# slab-local barrier after P2: 20th-of-32 arriver flushes its XCD's L2 early (returning arrival atomic overlapped with first poll), shrinking the wbl2 at the next global barrier
# baseline (speedup 1.0000x reference)
; __device__ __forceinline__ unsigned xb_ld(unsigned* p)              { return __hip_atomic_load(p, __ATOMIC_RELAXED, __HIP_MEMORY_SCOPE_AGENT); }
; __device__ __forceinline__ unsigned xb_add(unsigned* p, unsigned v) { return __hip_atomic_fetch_add(p, v, __ATOMIC_RELAXED, __HIP_MEMORY_SCOPE_AGENT); }
; #define XB_SPIN(cond, bar) do { unsigned _sp = 0; while (cond) { __builtin_amdgcn_s_sleep(1); \
;     if ((++_sp & 255u) == 0u) { if (xb_ld(&(bar)[XB_TMO])) break; if (_sp > XB_SPIN_CAP) { atomicAdd(&(bar)[XB_TMO], 1u); break; } } } } while (0)
; __device__ __forceinline__ void xcd_barrier(const XcdBarrier& b) {
;     ...
;         const unsigned old = xb_add(&bar[XB_XSUB(b.x)], 1u);
;         const unsigned gen = old / nloc;
;         if (old + 1u == (gen + 1u) * nloc) {
;             __builtin_amdgcn_fence(__ATOMIC_RELEASE, "agent");
;             asm volatile("s_waitcnt vmcnt(0)" ::: "memory");
;             const unsigned og = xb_add(&bar[XB_TOP], 1u);
;             const unsigned tg = og / nx;
;             if (og + 1u == (tg + 1u) * nx) xb_add(&bar[XB_TOPGEN], 1u);
;             else XB_SPIN(xb_ld(&bar[XB_TOPGEN]) == tg, bar);
;             __builtin_amdgcn_fence(__ATOMIC_ACQUIRE, "agent");
;             xb_add(&bar[XB_XGEN(b.x)], 1u);
;             asm volatile("s_waitcnt vmcnt(0)" ::: "memory");
;         } else {
;             XB_SPIN(xb_ld(&bar[XB_XGEN(b.x)]) == gen, bar);
.LBB0_261:
	s_cmp_eq_u32 s99, 0
	s_cbranch_scc1 .Lgbar_glob_2
	s_add_i32 s101, s101, 1
	s_add_u32 s4, s58, s98
	s_addc_u32 s5, s59, 0
	v_mov_b32_e32 v3, 1
	v_mov_b32_e32 v4, 0
	global_atomic_add v5, v4, v3, s[4:5] sc0
	v_mov_b32_e32 v6, s101
	v_lshlrev_b32_e32 v6, 5, v6
	s_nop 0
	global_load_dword v3, v4, s[4:5] sc1
	s_waitcnt vmcnt(0)
	v_add_u32_e32 v5, 13, v5
	v_cmp_ne_u32_e32 vcc, v5, v6
	v_mov_b32_e32 v5, 0
	s_cbranch_vccnz .Lgbar_lchk_2
	buffer_wbl2 sc1
	s_waitcnt vmcnt(0)
	s_branch .Lgbar_lloop_2
.Lgbar_lchk_2:
	v_cmp_ge_u32_e32 vcc, v3, v6
	s_cbranch_vccnz .Lgbar_ldone_2
